# scan item: LDS-DMA prefetch per operand region with full vmcnt drains at each barrier; egl via readlane
# speedup vs baseline: 1.0093x; 1.0093x over previous
.LBB0_487:
	s_and_b64 vcc, exec, s[0:1]
	s_cbranch_vccz .LBB0_397
	v_mov_b64_e32 v[4:5], s[16:17]
	flat_load_dwordx2 v[100:101], v[4:5]
	s_lshl_b32 s4, s75, 6
	s_and_b32 s0, s75, 1
	s_ashr_i32 s1, s75, 3
	s_and_b32 s4, s4, 0xffffff80
	s_ashr_i32 s5, s4, 31
	s_mul_i32 s8, s1, 0x3800000
	s_lshl_b32 s9, s0, 7
	s_lshl_b32 s18, s0, 13
	s_lshl_b32 s10, s75, 7
	s_and_b32 s10, s10, 0x300
	s_add_i32 s8, s8, s9
	s_add_i32 s8, s8, s10
	v_and_b32_e32 v22, 63, v198
	v_mov_b32_e32 v23, 0
	v_lshrrev_b32_e32 v24, 6, v198
	v_mov_b32_e32 v25, 0
	v_and_b32_e32 v26, 15, v198
	v_bfe_u32 v27, v198, 4, 2
	v_lshl_add_u32 v2, v22, 4, 0
	v_lshlrev_b32_e32 v131, 11, v24
	v_lshl_add_u32 v131, v22, 3, v131
	v_mul_u32_u24_e32 v114, 0x7000, v27
	v_lshl_add_u32 v114, v24, 5, v114
	v_lshl_add_u32 v114, v26, 1, v114
	v_add_u32_e32 v114, s8, v114
	s_nop 0
	v_readfirstlane_b32 s93, v24
	s_mov_b64 s[94:95], 0x4000
	s_mov_b64 s[96:97], 0x8000
	s_mov_b64 s[78:79], 0x400
	s_mov_b64 s[98:99], 0x800
	s_mov_b64 s[100:101], 0xc00
	s_lshl_b32 s88, s93, 12
	s_add_i32 s89, s88, 0x4000
	s_add_i32 s90, s88, 0x8000
	s_lshl_b32 s91, s93, 11
	s_add_i32 s92, s91, 0xe000
	s_add_i32 s91, s91, 0xc000
	s_lshl_b64 s[0:1], s[4:5], 2
	s_add_u32 s0, s0, 0x2ce00000
	s_addc_u32 s1, s1, 0
	s_movk_i32 s6, 0x7f
	v_mov_b32_e32 v4, 0
	v_mov_b32_e32 v5, v4
	v_mov_b32_e32 v6, v4
	v_mov_b32_e32 v7, v4
	v_mov_b32_e32 v16, v4
	v_mov_b32_e32 v17, v4
	v_mov_b32_e32 v18, v4
	v_mov_b32_e32 v19, v4
	v_mov_b32_e32 v44, v4
	v_mov_b32_e32 v45, v4
	v_mov_b32_e32 v46, v4
	v_mov_b32_e32 v47, v4
	v_mov_b32_e32 v76, v4
	v_mov_b32_e32 v77, v4
	v_mov_b32_e32 v78, v4
	v_mov_b32_e32 v79, v4
	v_mov_b32_e32 v84, v4
	v_mov_b32_e32 v85, v4
	v_mov_b32_e32 v86, v4
	v_mov_b32_e32 v87, v4
	v_mov_b32_e32 v88, v4
	v_mov_b32_e32 v89, v4
	v_mov_b32_e32 v90, v4
	v_mov_b32_e32 v91, v4
	v_mov_b32_e32 v92, v4
	v_mov_b32_e32 v93, v4
	v_mov_b32_e32 v94, v4
	v_mov_b32_e32 v95, v4
	v_mov_b32_e32 v96, v4
	v_mov_b32_e32 v97, v4
	v_mov_b32_e32 v98, v4
	v_mov_b32_e32 v99, v4
	s_waitcnt vmcnt(0) lgkmcnt(0)
	v_readfirstlane_b32 s86, v100
	v_readfirstlane_b32 s87, v101
	v_mad_i64_i32 v[28:29], s[10:11], s4, v210, v[100:101]
	v_lshl_add_u64 v[28:29], v[28:29], 0, s[34:35]
	v_lshl_add_u64 v[28:29], v[22:23], 4, v[28:29]
	v_lshlrev_b32_e32 v32, 12, v24
	v_mov_b32_e32 v33, 0
	v_lshl_add_u64 v[8:9], v[32:33], 0, v[28:29]
	v_lshl_add_u64 v[10:11], v[8:9], 0, s[94:95]
	v_lshl_add_u64 v[12:13], v[8:9], 0, s[96:97]
	v_lshlrev_b32_e32 v32, 11, v24
	v_lshl_add_u64 v[14:15], v[32:33], 0, v[28:29]
	s_add_u32 s10, s18, 0xe000
	s_mov_b32 s11, 0
	v_lshl_add_u64 v[20:21], v[14:15], 0, s[10:11]
	s_mov_b64 s[10:11], 0xc000
	v_lshl_add_u64 v[14:15], v[14:15], 0, s[10:11]
	v_lshl_add_u64 v[32:33], v[100:101], 0, s[0:1]
	v_lshl_add_u64 v[32:33], v[22:23], 2, v[32:33]
	global_load_dword v34, v[32:33], off
	global_load_dword v35, v[32:33], off offset:256
	s_mov_b32 m0, s88
	s_nop 0
	global_load_lds_dwordx4 v[8:9], off
	s_add_i32 m0, s88, 0x400
	v_lshl_add_u64 v[30:31], v[8:9], 0, s[78:79]
	global_load_lds_dwordx4 v[30:31], off
	s_add_i32 m0, s88, 0x800
	v_lshl_add_u64 v[30:31], v[8:9], 0, s[98:99]
	global_load_lds_dwordx4 v[30:31], off
	s_add_i32 m0, s88, 0xc00
	v_lshl_add_u64 v[30:31], v[8:9], 0, s[100:101]
	global_load_lds_dwordx4 v[30:31], off
	s_mov_b32 m0, s92
	s_nop 0
	global_load_lds_dwordx4 v[20:21], off
	s_add_i32 m0, s92, 0x400
	v_lshl_add_u64 v[30:31], v[20:21], 0, s[78:79]
	global_load_lds_dwordx4 v[30:31], off
	s_mov_b32 m0, s89
	s_nop 0
	global_load_lds_dwordx4 v[10:11], off
	s_add_i32 m0, s89, 0x400
	v_lshl_add_u64 v[30:31], v[10:11], 0, s[78:79]
	global_load_lds_dwordx4 v[30:31], off
	s_add_i32 m0, s89, 0x800
	v_lshl_add_u64 v[30:31], v[10:11], 0, s[98:99]
	global_load_lds_dwordx4 v[30:31], off
	s_add_i32 m0, s89, 0xc00
	v_lshl_add_u64 v[30:31], v[10:11], 0, s[100:101]
	global_load_lds_dwordx4 v[30:31], off
	s_mov_b32 m0, s91
	s_nop 0
	global_load_lds_dwordx4 v[14:15], off
	s_add_i32 m0, s91, 0x400
	v_lshl_add_u64 v[30:31], v[14:15], 0, s[78:79]
	global_load_lds_dwordx4 v[30:31], off
	s_mov_b32 m0, s90
	s_nop 0
	global_load_lds_dwordx4 v[12:13], off
	s_add_i32 m0, s90, 0x400
	v_lshl_add_u64 v[30:31], v[12:13], 0, s[78:79]
	global_load_lds_dwordx4 v[30:31], off
	s_add_i32 m0, s90, 0x800
	v_lshl_add_u64 v[30:31], v[12:13], 0, s[98:99]
	global_load_lds_dwordx4 v[30:31], off
	s_add_i32 m0, s90, 0xc00
	v_lshl_add_u64 v[30:31], v[12:13], 0, s[100:101]
	global_load_lds_dwordx4 v[30:31], off
	v_lshl_add_u64 v[8:9], v[8:9], 0, s[50:51]
	v_lshl_add_u64 v[10:11], v[10:11], 0, s[50:51]
	v_lshl_add_u64 v[12:13], v[12:13], 0, s[50:51]
	v_lshl_add_u64 v[14:15], v[14:15], 0, s[50:51]
	v_lshl_add_u64 v[20:21], v[20:21], 0, s[50:51]
	s_waitcnt vmcnt(0)
	s_barrier
.Lsc_step:
	ds_read_b128 v[212:215], v2
	ds_read_b128 v[216:219], v2 offset:4096
	ds_read_b128 v[220:223], v2 offset:8192
	ds_read_b128 v[224:227], v2 offset:12288
	ds_read_b128 v[228:231], v2 offset:1024
	ds_read2st64_b64 v[188:191], v131 offset0:112 offset1:113
	ds_read2st64_b64 v[192:195], v131 offset0:114 offset1:115
	v_cvt_pk_bf16_f32 v132, v16, v17
	v_cvt_pk_bf16_f32 v133, v18, v19
	v_cvt_pk_bf16_f32 v134, v4, v5
	v_cvt_pk_bf16_f32 v135, v6, v7
	v_cvt_pk_bf16_f32 v136, v44, v45
	v_cvt_pk_bf16_f32 v137, v46, v47
	v_cvt_pk_bf16_f32 v138, v76, v77
	v_cvt_pk_bf16_f32 v139, v78, v79
	v_cvt_pk_bf16_f32 v140, v84, v85
	v_cvt_pk_bf16_f32 v141, v86, v87
	v_cvt_pk_bf16_f32 v142, v88, v89
	v_cvt_pk_bf16_f32 v143, v90, v91
	v_cvt_pk_bf16_f32 v144, v92, v93
	v_cvt_pk_bf16_f32 v145, v94, v95
	v_cvt_pk_bf16_f32 v146, v96, v97
	v_cvt_pk_bf16_f32 v147, v98, v99
	v_add_u32_e32 v197, 0x4000c00, v114
	s_waitcnt lgkmcnt(6)
	v_mfma_f32_16x16x32_bf16 v[156:159], v[212:215], v[132:135], 0
	ds_read_b128 v[232:235], v2 offset:5120
	s_waitcnt lgkmcnt(6)
	v_mfma_f32_16x16x32_bf16 v[160:163], v[216:219], v[132:135], 0
	ds_read_b128 v[236:239], v2 offset:9216
	s_waitcnt lgkmcnt(6)
	v_mfma_f32_16x16x32_bf16 v[164:167], v[220:223], v[132:135], 0
	ds_read_b128 v[212:215], v2 offset:13312
	s_waitcnt lgkmcnt(6)
	v_mfma_f32_16x16x32_bf16 v[168:171], v[224:227], v[132:135], 0
	ds_read_b128 v[216:219], v2 offset:2048
	s_waitcnt lgkmcnt(6)
	v_mfma_f32_16x16x32_bf16 v[156:159], v[228:231], v[136:139], v[156:159]
	ds_read_b128 v[220:223], v2 offset:6144
	s_waitcnt lgkmcnt(4)
	v_mfma_f32_16x16x32_bf16 v[160:163], v[232:235], v[136:139], v[160:163]
	ds_read_b128 v[224:227], v2 offset:10240
	s_waitcnt lgkmcnt(4)
	v_mfma_f32_16x16x32_bf16 v[164:167], v[236:239], v[136:139], v[164:167]
	ds_read_b128 v[228:231], v2 offset:14336
	s_waitcnt lgkmcnt(4)
	v_mfma_f32_16x16x32_bf16 v[168:171], v[212:215], v[136:139], v[168:171]
	ds_read_b128 v[232:235], v2 offset:3072
	s_waitcnt lgkmcnt(4)
	v_mfma_f32_16x16x32_bf16 v[156:159], v[216:219], v[140:143], v[156:159]
	ds_read_b128 v[236:239], v2 offset:7168
	s_waitcnt lgkmcnt(4)
	v_mfma_f32_16x16x32_bf16 v[160:163], v[220:223], v[140:143], v[160:163]
	ds_read_b128 v[212:215], v2 offset:11264
	s_waitcnt lgkmcnt(4)
	v_mfma_f32_16x16x32_bf16 v[164:167], v[224:227], v[140:143], v[164:167]
	ds_read_b128 v[216:219], v2 offset:15360
	s_waitcnt lgkmcnt(4)
	v_mfma_f32_16x16x32_bf16 v[168:171], v[228:231], v[140:143], v[168:171]
	s_waitcnt lgkmcnt(3)
	v_mfma_f32_16x16x32_bf16 v[156:159], v[232:235], v[144:147], v[156:159]
	s_waitcnt lgkmcnt(2)
	v_mfma_f32_16x16x32_bf16 v[160:163], v[236:239], v[144:147], v[160:163]
	s_waitcnt lgkmcnt(1)
	v_mfma_f32_16x16x32_bf16 v[164:167], v[212:215], v[144:147], v[164:167]
	s_waitcnt lgkmcnt(0)
	v_mfma_f32_16x16x32_bf16 v[168:171], v[216:219], v[144:147], v[168:171]
	s_waitcnt lgkmcnt(0)
	s_waitcnt vmcnt(0)
	s_barrier
	s_cmp_eq_u32 s6, 0
	s_cbranch_scc1 .Lsc_skip1
	s_mov_b32 m0, s88
	s_nop 0
	global_load_lds_dwordx4 v[8:9], off
	s_add_i32 m0, s88, 0x400
	v_lshl_add_u64 v[30:31], v[8:9], 0, s[78:79]
	global_load_lds_dwordx4 v[30:31], off
	s_add_i32 m0, s88, 0x800
	v_lshl_add_u64 v[30:31], v[8:9], 0, s[98:99]
	global_load_lds_dwordx4 v[30:31], off
	s_add_i32 m0, s88, 0xc00
	v_lshl_add_u64 v[30:31], v[8:9], 0, s[100:101]
	global_load_lds_dwordx4 v[30:31], off
	s_mov_b32 m0, s92
	s_nop 0
	global_load_lds_dwordx4 v[20:21], off
	s_add_i32 m0, s92, 0x400
	v_lshl_add_u64 v[30:31], v[20:21], 0, s[78:79]
	global_load_lds_dwordx4 v[30:31], off
.Lsc_skip1:
	ds_read_b128 v[220:223], v2 offset:16384
	ds_read_b128 v[224:227], v2 offset:20480
	ds_read_b128 v[228:231], v2 offset:24576
	ds_read_b128 v[232:235], v2 offset:28672
	ds_read_b128 v[236:239], v2 offset:17408
	s_sub_i32 s10, 0x7f, s6
	s_and_b32 s11, s10, 63
	v_readlane_b32 s96, v34, s11
	v_readlane_b32 s97, v35, s11
	s_nop 1
	s_cmp_lt_u32 s10, 64
	s_cselect_b32 s96, s96, s97
	v_mov_b32_e32 v196, s96
	s_waitcnt lgkmcnt(4)
	v_mfma_f32_16x16x32_bf16 v[172:175], v[220:223], v[132:135], 0
	ds_read_b128 v[212:215], v2 offset:21504
	v_pk_mul_f32 v[16:17], v[16:17], v[196:197] op_sel_hi:[1,0]
	v_pk_mul_f32 v[18:19], v[18:19], v[196:197] op_sel_hi:[1,0]
	s_waitcnt lgkmcnt(4)
	v_mfma_f32_16x16x32_bf16 v[176:179], v[224:227], v[132:135], 0
	ds_read_b128 v[216:219], v2 offset:25600
	v_pk_mul_f32 v[4:5], v[4:5], v[196:197] op_sel_hi:[1,0]
	v_pk_mul_f32 v[6:7], v[6:7], v[196:197] op_sel_hi:[1,0]
	s_waitcnt lgkmcnt(4)
	v_mfma_f32_16x16x32_bf16 v[180:183], v[228:231], v[132:135], 0
	ds_read_b128 v[220:223], v2 offset:29696
	v_pk_mul_f32 v[44:45], v[44:45], v[196:197] op_sel_hi:[1,0]
	v_pk_mul_f32 v[46:47], v[46:47], v[196:197] op_sel_hi:[1,0]
	v_lshlrev_b32_e32 v240, 16, v188
	v_and_b32_e32 v241, 0xffff0000, v188
	v_lshlrev_b32_e32 v242, 16, v189
	v_and_b32_e32 v243, 0xffff0000, v189
	s_waitcnt lgkmcnt(4)
	v_mfma_f32_16x16x32_bf16 v[184:187], v[232:235], v[132:135], 0
	ds_read_b128 v[224:227], v2 offset:18432
	v_pk_mul_f32 v[76:77], v[76:77], v[196:197] op_sel_hi:[1,0]
	v_pk_mul_f32 v[78:79], v[78:79], v[196:197] op_sel_hi:[1,0]
	v_sub_f32_e32 v156, v240, v156
	v_sub_f32_e32 v157, v241, v157
	v_sub_f32_e32 v158, v242, v158
	v_sub_f32_e32 v159, v243, v159
	s_waitcnt lgkmcnt(4)
	v_mfma_f32_16x16x32_bf16 v[172:175], v[236:239], v[136:139], v[172:175]
	ds_read_b128 v[228:231], v2 offset:22528
	v_pk_mul_f32 v[84:85], v[84:85], v[196:197] op_sel_hi:[1,0]
	v_pk_mul_f32 v[86:87], v[86:87], v[196:197] op_sel_hi:[1,0]
	v_lshlrev_b32_e32 v240, 16, v190
	v_and_b32_e32 v241, 0xffff0000, v190
	v_lshlrev_b32_e32 v242, 16, v191
	v_and_b32_e32 v243, 0xffff0000, v191
	s_waitcnt lgkmcnt(4)
	v_mfma_f32_16x16x32_bf16 v[176:179], v[212:215], v[136:139], v[176:179]
	ds_read_b128 v[232:235], v2 offset:26624
	v_pk_mul_f32 v[88:89], v[88:89], v[196:197] op_sel_hi:[1,0]
	v_pk_mul_f32 v[90:91], v[90:91], v[196:197] op_sel_hi:[1,0]
	v_sub_f32_e32 v160, v240, v160
	v_sub_f32_e32 v161, v241, v161
	v_sub_f32_e32 v162, v242, v162
	v_sub_f32_e32 v163, v243, v163
	s_waitcnt lgkmcnt(4)
	v_mfma_f32_16x16x32_bf16 v[180:183], v[216:219], v[136:139], v[180:183]
	ds_read_b128 v[236:239], v2 offset:30720
	v_pk_mul_f32 v[92:93], v[92:93], v[196:197] op_sel_hi:[1,0]
	v_pk_mul_f32 v[94:95], v[94:95], v[196:197] op_sel_hi:[1,0]
	v_lshlrev_b32_e32 v240, 16, v192
	v_and_b32_e32 v241, 0xffff0000, v192
	v_lshlrev_b32_e32 v242, 16, v193
	v_and_b32_e32 v243, 0xffff0000, v193
	v_cvt_pk_bf16_f32 v148, v156, v157
	v_cvt_pk_bf16_f32 v149, v158, v159
	v_cvt_pk_bf16_f32 v150, v160, v161
	v_cvt_pk_bf16_f32 v151, v162, v163
	s_waitcnt lgkmcnt(4)
	v_mfma_f32_16x16x32_bf16 v[184:187], v[220:223], v[136:139], v[184:187]
	ds_read_b128 v[212:215], v2 offset:19456
	v_pk_mul_f32 v[96:97], v[96:97], v[196:197] op_sel_hi:[1,0]
	v_pk_mul_f32 v[98:99], v[98:99], v[196:197] op_sel_hi:[1,0]
	v_sub_f32_e32 v164, v240, v164
	v_sub_f32_e32 v165, v241, v165
	v_sub_f32_e32 v166, v242, v166
	v_sub_f32_e32 v167, v243, v167
	s_waitcnt lgkmcnt(4)
	v_mfma_f32_16x16x32_bf16 v[172:175], v[224:227], v[140:143], v[172:175]
	ds_read_b128 v[216:219], v2 offset:23552
	v_lshlrev_b32_e32 v240, 16, v194
	v_and_b32_e32 v241, 0xffff0000, v194
	v_lshlrev_b32_e32 v242, 16, v195
	v_and_b32_e32 v243, 0xffff0000, v195
	s_waitcnt lgkmcnt(4)
	v_mfma_f32_16x16x32_bf16 v[176:179], v[228:231], v[140:143], v[176:179]
	ds_read_b128 v[220:223], v2 offset:27648
	v_sub_f32_e32 v168, v240, v168
	v_sub_f32_e32 v169, v241, v169
	v_sub_f32_e32 v170, v242, v170
	v_sub_f32_e32 v171, v243, v171
	s_waitcnt lgkmcnt(4)
	v_mfma_f32_16x16x32_bf16 v[180:183], v[232:235], v[140:143], v[180:183]
	ds_read_b128 v[224:227], v2 offset:31744
	v_cvt_pk_bf16_f32 v152, v164, v165
	v_cvt_pk_bf16_f32 v153, v166, v167
	v_cvt_pk_bf16_f32 v154, v168, v169
	v_cvt_pk_bf16_f32 v155, v170, v171
	s_waitcnt lgkmcnt(4)
	v_mfma_f32_16x16x32_bf16 v[184:187], v[236:239], v[140:143], v[184:187]
	s_waitcnt lgkmcnt(3)
	v_mfma_f32_16x16x32_bf16 v[172:175], v[212:215], v[144:147], v[172:175]
	s_waitcnt lgkmcnt(2)
	v_mfma_f32_16x16x32_bf16 v[176:179], v[216:219], v[144:147], v[176:179]
	s_waitcnt lgkmcnt(1)
	v_mfma_f32_16x16x32_bf16 v[180:183], v[220:223], v[144:147], v[180:183]
	s_waitcnt lgkmcnt(0)
	v_mfma_f32_16x16x32_bf16 v[184:187], v[224:227], v[144:147], v[184:187]
	s_waitcnt lgkmcnt(0)
	s_cmp_eq_u32 s6, 0
	s_cbranch_scc1 .Lsc_last2
	s_waitcnt vmcnt(0)
	s_barrier
	s_mov_b32 m0, s89
	s_nop 0
	global_load_lds_dwordx4 v[10:11], off
	s_add_i32 m0, s89, 0x400
	v_lshl_add_u64 v[30:31], v[10:11], 0, s[78:79]
	global_load_lds_dwordx4 v[30:31], off
	s_add_i32 m0, s89, 0x800
	v_lshl_add_u64 v[30:31], v[10:11], 0, s[98:99]
	global_load_lds_dwordx4 v[30:31], off
	s_add_i32 m0, s89, 0xc00
	v_lshl_add_u64 v[30:31], v[10:11], 0, s[100:101]
	global_load_lds_dwordx4 v[30:31], off
	s_branch .Lsc_p3
.Lsc_last2:
	s_waitcnt vmcnt(0)
	s_barrier
.Lsc_p3:
	ds_read_b128 v[228:231], v2 offset:49152
	ds_read_b128 v[232:235], v2 offset:51200
	ds_read_b128 v[236:239], v2 offset:53248
	ds_read_b128 v[212:215], v2 offset:55296
	ds_read_b128 v[216:219], v2 offset:50176
	s_waitcnt lgkmcnt(4)
	v_mfma_f32_16x16x32_bf16 v[172:175], v[228:231], v[148:151], v[172:175]
	ds_read_b128 v[220:223], v2 offset:52224
	s_waitcnt lgkmcnt(4)
	v_mfma_f32_16x16x32_bf16 v[176:179], v[232:235], v[148:151], v[176:179]
	ds_read_b128 v[224:227], v2 offset:54272
	s_waitcnt lgkmcnt(4)
	v_mfma_f32_16x16x32_bf16 v[180:183], v[236:239], v[148:151], v[180:183]
	ds_read_b128 v[228:231], v2 offset:56320
	s_waitcnt lgkmcnt(4)
	v_mfma_f32_16x16x32_bf16 v[184:187], v[212:215], v[148:151], v[184:187]
	ds_read_b128 v[232:235], v2 offset:32768
	s_waitcnt lgkmcnt(4)
	v_mfma_f32_16x16x32_bf16 v[172:175], v[216:219], v[152:155], v[172:175]
	ds_read_b128 v[236:239], v2 offset:34816
	s_waitcnt lgkmcnt(4)
	v_mfma_f32_16x16x32_bf16 v[176:179], v[220:223], v[152:155], v[176:179]
	ds_read_b128 v[212:215], v2 offset:36864
	s_waitcnt lgkmcnt(4)
	v_mfma_f32_16x16x32_bf16 v[180:183], v[224:227], v[152:155], v[180:183]
	ds_read_b128 v[216:219], v2 offset:38912
	s_waitcnt lgkmcnt(4)
	v_mfma_f32_16x16x32_bf16 v[184:187], v[228:231], v[152:155], v[184:187]
	ds_read_b128 v[220:223], v2 offset:40960
	s_waitcnt lgkmcnt(4)
	v_mfma_f32_16x16x32_bf16 v[16:19], v[232:235], v[148:151], v[16:19]
	ds_read_b128 v[224:227], v2 offset:43008
	s_waitcnt lgkmcnt(4)
	v_mfma_f32_16x16x32_bf16 v[4:7], v[236:239], v[148:151], v[4:7]
	ds_read_b128 v[228:231], v2 offset:45056
	v_bfe_u32 v156, v172, 16, 1
	v_add3_u32 v156, v172, v156, s43
	global_store_short_d16_hi v197, v156, s[86:87]
	v_bfe_u32 v157, v173, 16, 1
	v_add3_u32 v157, v173, v157, s43
	v_add_u32_e32 v189, 0x1c00, v197
	global_store_short_d16_hi v189, v157, s[86:87]
	s_waitcnt lgkmcnt(4)
	v_mfma_f32_16x16x32_bf16 v[44:47], v[212:215], v[148:151], v[44:47]
	ds_read_b128 v[232:235], v2 offset:47104
	v_bfe_u32 v158, v174, 16, 1
	v_add3_u32 v158, v174, v158, s43
	v_add_u32_e32 v190, 0x3800, v197
	global_store_short_d16_hi v190, v158, s[86:87]
	v_bfe_u32 v159, v175, 16, 1
	v_add3_u32 v159, v175, v159, s43
	v_add_u32_e32 v191, 0x5400, v197
	global_store_short_d16_hi v191, v159, s[86:87]
	s_waitcnt lgkmcnt(4)
	v_mfma_f32_16x16x32_bf16 v[76:79], v[216:219], v[148:151], v[76:79]
	ds_read_b128 v[236:239], v2 offset:33792
	s_waitcnt lgkmcnt(4)
	v_mfma_f32_16x16x32_bf16 v[84:87], v[220:223], v[148:151], v[84:87]
	ds_read_b128 v[212:215], v2 offset:35840
	v_bfe_u32 v160, v176, 16, 1
	v_add3_u32 v160, v176, v160, s43
	v_add_u32_e32 v192, 0x1c000, v197
	global_store_short_d16_hi v192, v160, s[86:87]
	v_bfe_u32 v161, v177, 16, 1
	v_add3_u32 v161, v177, v161, s43
	v_add_u32_e32 v193, 0x1dc00, v197
	global_store_short_d16_hi v193, v161, s[86:87]
	s_waitcnt lgkmcnt(4)
	v_mfma_f32_16x16x32_bf16 v[88:91], v[224:227], v[148:151], v[88:91]
	ds_read_b128 v[216:219], v2 offset:37888
	v_bfe_u32 v162, v178, 16, 1
	v_add3_u32 v162, v178, v162, s43
	v_add_u32_e32 v194, 0x1f800, v197
	global_store_short_d16_hi v194, v162, s[86:87]
	v_bfe_u32 v163, v179, 16, 1
	v_add3_u32 v163, v179, v163, s43
	v_add_u32_e32 v195, 0x21400, v197
	global_store_short_d16_hi v195, v163, s[86:87]
	s_waitcnt lgkmcnt(4)
	v_mfma_f32_16x16x32_bf16 v[92:95], v[228:231], v[148:151], v[92:95]
	ds_read_b128 v[220:223], v2 offset:39936
	s_waitcnt lgkmcnt(4)
	v_mfma_f32_16x16x32_bf16 v[96:99], v[232:235], v[148:151], v[96:99]
	ds_read_b128 v[224:227], v2 offset:41984
	v_bfe_u32 v156, v180, 16, 1
	v_add3_u32 v156, v180, v156, s43
	v_add_u32_e32 v188, 0x38000, v197
	global_store_short_d16_hi v188, v156, s[86:87]
	v_bfe_u32 v157, v181, 16, 1
	v_add3_u32 v157, v181, v157, s43
	v_add_u32_e32 v189, 0x39c00, v197
	global_store_short_d16_hi v189, v157, s[86:87]
	s_waitcnt lgkmcnt(4)
	v_mfma_f32_16x16x32_bf16 v[16:19], v[236:239], v[152:155], v[16:19]
	ds_read_b128 v[228:231], v2 offset:44032
	v_bfe_u32 v158, v182, 16, 1
	v_add3_u32 v158, v182, v158, s43
	v_add_u32_e32 v190, 0x3b800, v197
	global_store_short_d16_hi v190, v158, s[86:87]
	v_bfe_u32 v159, v183, 16, 1
	v_add3_u32 v159, v183, v159, s43
	v_add_u32_e32 v191, 0x3d400, v197
	global_store_short_d16_hi v191, v159, s[86:87]
	s_waitcnt lgkmcnt(4)
	v_mfma_f32_16x16x32_bf16 v[4:7], v[212:215], v[152:155], v[4:7]
	ds_read_b128 v[232:235], v2 offset:46080
	s_waitcnt lgkmcnt(4)
	v_mfma_f32_16x16x32_bf16 v[44:47], v[216:219], v[152:155], v[44:47]
	ds_read_b128 v[236:239], v2 offset:48128
	v_bfe_u32 v160, v184, 16, 1
	v_add3_u32 v160, v184, v160, s43
	v_add_u32_e32 v192, 0x54000, v197
	global_store_short_d16_hi v192, v160, s[86:87]
	v_bfe_u32 v161, v185, 16, 1
	v_add3_u32 v161, v185, v161, s43
	v_add_u32_e32 v193, 0x55c00, v197
	global_store_short_d16_hi v193, v161, s[86:87]
	s_waitcnt lgkmcnt(4)
	v_mfma_f32_16x16x32_bf16 v[76:79], v[220:223], v[152:155], v[76:79]
	v_bfe_u32 v162, v186, 16, 1
	v_add3_u32 v162, v186, v162, s43
	v_add_u32_e32 v194, 0x57800, v197
	global_store_short_d16_hi v194, v162, s[86:87]
	v_bfe_u32 v163, v187, 16, 1
	v_add3_u32 v163, v187, v163, s43
	v_add_u32_e32 v195, 0x59400, v197
	global_store_short_d16_hi v195, v163, s[86:87]
	s_waitcnt lgkmcnt(3)
	v_mfma_f32_16x16x32_bf16 v[84:87], v[224:227], v[152:155], v[84:87]
	s_waitcnt lgkmcnt(2)
	v_mfma_f32_16x16x32_bf16 v[88:91], v[228:231], v[152:155], v[88:91]
	s_waitcnt lgkmcnt(1)
	v_mfma_f32_16x16x32_bf16 v[92:95], v[232:235], v[152:155], v[92:95]
	s_waitcnt lgkmcnt(0)
	v_mfma_f32_16x16x32_bf16 v[96:99], v[236:239], v[152:155], v[96:99]
	s_waitcnt lgkmcnt(0)
	s_waitcnt vmcnt(0)
	s_barrier
	s_cmp_eq_u32 s6, 0
	s_cbranch_scc1 .LBB0_397
	s_mov_b32 m0, s91
	s_nop 0
	global_load_lds_dwordx4 v[14:15], off
	s_add_i32 m0, s91, 0x400
	v_lshl_add_u64 v[30:31], v[14:15], 0, s[78:79]
	global_load_lds_dwordx4 v[30:31], off
	s_mov_b32 m0, s90
	s_nop 0
	global_load_lds_dwordx4 v[12:13], off
	s_add_i32 m0, s90, 0x400
	v_lshl_add_u64 v[30:31], v[12:13], 0, s[78:79]
	global_load_lds_dwordx4 v[30:31], off
	s_add_i32 m0, s90, 0x800
	v_lshl_add_u64 v[30:31], v[12:13], 0, s[98:99]
	global_load_lds_dwordx4 v[30:31], off
	s_add_i32 m0, s90, 0xc00
	v_lshl_add_u64 v[30:31], v[12:13], 0, s[100:101]
	global_load_lds_dwordx4 v[30:31], off
	s_add_u32 s0, s0, 4
	s_addc_u32 s1, s1, 0
	s_add_i32 s6, s6, -1
	v_add_u32_e32 v114, 0x70000, v114
	v_lshl_add_u64 v[8:9], v[8:9], 0, s[50:51]
	v_lshl_add_u64 v[10:11], v[10:11], 0, s[50:51]
	v_lshl_add_u64 v[12:13], v[12:13], 0, s[50:51]
	v_lshl_add_u64 v[14:15], v[14:15], 0, s[50:51]
	v_lshl_add_u64 v[20:21], v[20:21], 0, s[50:51]
	s_branch .Lsc_step
